# v33 + P2 compressed-attention pass-1 row max as a 8-op v_max3 tree (no canonicalising self-max)
# speedup vs baseline: 1.0028x; 1.0028x over previous
; __device__ __forceinline__ float ex2(float x) { return __builtin_amdgcn_exp2f(x); }
; __device__ __forceinline__ void cmp_task_lds(const Prm& P, Ctx& C, int b, int kvh, int tg, CStream& CS, const LAS bf16_t* wlb, const int NGW, bf16x8 (&qnx)[4], int& qnx_tg, const int tg_next) {
;     ...
;         if (tile < nfull) {
;             const float tmax = fmaxf(fmaxf(fmaxf(fmaxf(S[0], S[1]), fmaxf(S[2], S[3])), fmaxf(fmaxf(S[4], S[5]), fmaxf(S[6], S[7]))), fmaxf(fmaxf(fmaxf(S[8], S[9]), fmaxf(S[10], S[11])), fmaxf(fmaxf(S[12], S[13]), fmaxf(S[14], S[15]))));
;             const float mn = fmaxf(m, tmax);
;             float e[16];
; #pragma unroll
;             for (int r = 0; r < 16; ++r) e[r] = ex2(S[r] - mn);
;             const float ps = (((e[0] + e[1]) + (e[2] + e[3])) + ((e[4] + e[5]) + (e[6] + e[7]))) + (((e[8] + e[9]) + (e[10] + e[11])) + ((e[12] + e[13]) + (e[14] + e[15])));
;             l = l * ex2(m - mn) + ps; m = mn;
.LBB0_1238:
	s_andn2_b64 vcc, exec, s[0:1]
	s_cbranch_vccnz .LBB0_1240
	s_nop 6
	v_max3_f32 v20, v2, v3, v4
	v_max3_f32 v21, v7, v8, v9
	v_max3_f32 v28, v12, v13, v14
	v_max3_f32 v20, v20, v5, v6
	v_max3_f32 v21, v21, v10, v11
	v_max3_f32 v28, v28, v15, v16
	v_max3_f32 v20, v20, v21, v17
	v_max3_f32 v21, v27, v20, v28
	v_sub_f32_e32 v3, v3, v21
	v_exp_f32_e32 v28, v3
	v_sub_f32_e32 v3, v4, v21
	v_exp_f32_e32 v4, v3
	v_sub_f32_e32 v3, v5, v21
	v_exp_f32_e32 v30, v3
	v_sub_f32_e32 v3, v6, v21
	v_exp_f32_e32 v6, v3
	v_sub_f32_e32 v3, v7, v21
	v_exp_f32_e32 v32, v3
	v_sub_f32_e32 v3, v8, v21
	v_exp_f32_e32 v8, v3
	v_sub_f32_e32 v3, v9, v21
	v_sub_f32_e32 v5, v11, v21
	v_sub_f32_e32 v2, v2, v21
	v_exp_f32_e32 v34, v3
	v_sub_f32_e32 v3, v10, v21
	v_exp_f32_e32 v29, v5
	v_sub_f32_e32 v5, v12, v21
	v_sub_f32_e32 v7, v13, v21
	v_sub_f32_e32 v9, v15, v21
	v_exp_f32_e32 v2, v2
	v_exp_f32_e32 v3, v3
	v_exp_f32_e32 v5, v5
	v_exp_f32_e32 v31, v7
	v_sub_f32_e32 v7, v14, v21
	v_exp_f32_e32 v33, v9
	v_sub_f32_e32 v9, v16, v21
	v_sub_f32_e32 v10, v17, v21
	v_exp_f32_e32 v7, v7
	v_exp_f32_e32 v9, v9
	v_exp_f32_e32 v35, v10
	v_pk_add_f32 v[2:3], v[2:3], v[28:29]
	v_pk_add_f32 v[4:5], v[4:5], v[30:31]
	s_nop 0
	v_pk_add_f32 v[2:3], v[2:3], v[4:5]
	v_pk_add_f32 v[4:5], v[6:7], v[32:33]
	v_pk_add_f32 v[6:7], v[8:9], v[34:35]
	s_nop 0
	v_pk_add_f32 v[4:5], v[4:5], v[6:7]
	s_nop 0
	v_pk_add_f32 v[2:3], v[2:3], v[4:5]
	s_nop 0
	v_add_f32_e32 v20, v2, v3
